# final RMSNorm pass: gain vector loads hoisted out of the row loop, two rows per iteration with all loads issued together and next pair prefetched (was 4 serialized load-wait rounds per row)
# speedup vs baseline: 1.0101x; 1.0101x over previous
.LBB0_1097:
	global_load_dwordx4 v[24:27], v[2:3], off
	global_load_dwordx4 v[28:31], v[2:3], off offset:16
	global_load_dwordx4 v[32:35], v[2:3], off offset:2048
	global_load_dwordx4 v[36:39], v[2:3], off offset:2064
	s_add_u32 s10, s72, s7
	s_addc_u32 s11, s73, s8
	global_load_dwordx2 v[18:19], v1, s[10:11]
	s_add_u32 s10, s10, s0
	s_addc_u32 s11, s11, s1
	global_load_dwordx2 v[64:65], v1, s[10:11]
	v_lshl_add_u64 v[16:17], s[72:73], 0, v[4:5]
	v_add_co_u32_e32 v16, vcc, s9, v16
	s_nop 1
	v_addc_co_u32_e32 v17, vcc, 0, v17, vcc
	global_load_dwordx4 v[8:11], v[16:17], off
	global_load_dwordx4 v[40:43], v[16:17], off offset:1024
	v_lshl_add_u64 v[106:107], v[16:17], 0, s[2:3]
	global_load_dwordx4 v[66:69], v[106:107], off
	global_load_dwordx4 v[70:73], v[106:107], off offset:1024
	s_add_u32 s7, s7, s0
	s_addc_u32 s8, s8, s1
	s_add_u32 s7, s7, s0
	s_addc_u32 s8, s8, s1
	v_lshl_add_u64 v[4:5], v[4:5], 0, s[2:3]
	v_lshl_add_u64 v[4:5], v[4:5], 0, s[2:3]
	s_add_i32 s6, s6, s12
	s_add_i32 s6, s6, s12
	s_waitcnt vmcnt(0)
	s_branch .Lfn_body
.Lfn_loop:
	s_waitcnt vmcnt(8)
.Lfn_body:
	v_mov_b64_e32 v[44:45], v[18:19]
	v_mov_b64_e32 v[46:47], v[8:9]
	v_mov_b64_e32 v[48:49], v[10:11]
	v_mov_b64_e32 v[50:51], v[40:41]
	v_mov_b64_e32 v[52:53], v[42:43]
	v_mov_b64_e32 v[74:75], v[64:65]
	v_mov_b64_e32 v[76:77], v[66:67]
	v_mov_b64_e32 v[78:79], v[68:69]
	v_mov_b64_e32 v[80:81], v[70:71]
	v_mov_b64_e32 v[82:83], v[72:73]
	s_cmpk_gt_i32 s6, 0x7fff
	s_cselect_b32 s14, 1, 0
	s_cbranch_scc1 .Lfn_nopf
	s_add_u32 s10, s72, s7
	s_addc_u32 s11, s73, s8
	global_load_dwordx2 v[18:19], v1, s[10:11]
	s_add_u32 s10, s10, s0
	s_addc_u32 s11, s11, s1
	global_load_dwordx2 v[64:65], v1, s[10:11]
	v_lshl_add_u64 v[16:17], s[72:73], 0, v[4:5]
	v_add_co_u32_e32 v16, vcc, s9, v16
	s_nop 1
	v_addc_co_u32_e32 v17, vcc, 0, v17, vcc
	global_load_dwordx4 v[8:11], v[16:17], off
	global_load_dwordx4 v[40:43], v[16:17], off offset:1024
	v_lshl_add_u64 v[106:107], v[16:17], 0, s[2:3]
	global_load_dwordx4 v[66:69], v[106:107], off
	global_load_dwordx4 v[70:73], v[106:107], off offset:1024
	s_add_u32 s7, s7, s0
	s_addc_u32 s8, s8, s1
	s_add_u32 s7, s7, s0
	s_addc_u32 s8, s8, s1
	v_lshl_add_u64 v[4:5], v[4:5], 0, s[2:3]
	v_lshl_add_u64 v[4:5], v[4:5], 0, s[2:3]
	s_add_i32 s6, s6, s12
	s_add_i32 s6, s6, s12
.Lfn_nopf:
	v_lshl_add_u64 v[108:109], v[6:7], 0, s[4:5]
	v_ffbh_u32_e32 v102, v45
	v_min_u32_e32 v102, 32, v102
	v_lshlrev_b64 v[104:105], v102, v[44:45]
	v_min_u32_e32 v104, 1, v104
	v_or_b32_e32 v104, v105, v104
	v_cvt_f32_u32_e32 v104, v104
	v_sub_u32_e32 v102, 32, v102
	v_ldexp_f32 v104, v104, v102
	v_mul_f32_e32 v104, 0x37800000, v104
	v_fmamk_f32 v104, v104, 0x3a800000, v0
	v_rsq_f32_e32 v54, v104
	v_lshlrev_b32_e32 v12, 16, v46
	v_and_b32_e32 v13, 0xffff0000, v46
	v_lshlrev_b32_e32 v14, 16, v47
	v_and_b32_e32 v15, 0xffff0000, v47
	v_pk_mul_f32 v[12:13], v[54:55], v[12:13] op_sel_hi:[0,1]
	v_pk_mul_f32 v[14:15], v[54:55], v[14:15] op_sel_hi:[0,1]
	v_pk_mul_f32 v[12:13], v[24:25], v[12:13]
	v_pk_mul_f32 v[14:15], v[26:27], v[14:15]
	global_store_dwordx4 v[6:7], v[12:15], off offset:-2064 nt
	v_lshlrev_b32_e32 v20, 16, v48
	v_and_b32_e32 v21, 0xffff0000, v48
	v_lshlrev_b32_e32 v22, 16, v49
	v_and_b32_e32 v23, 0xffff0000, v49
	v_pk_mul_f32 v[20:21], v[54:55], v[20:21] op_sel_hi:[0,1]
	v_pk_mul_f32 v[22:23], v[54:55], v[22:23] op_sel_hi:[0,1]
	v_pk_mul_f32 v[20:21], v[28:29], v[20:21]
	v_pk_mul_f32 v[22:23], v[30:31], v[22:23]
	global_store_dwordx4 v[6:7], v[20:23], off offset:-2048 nt
	v_lshlrev_b32_e32 v56, 16, v50
	v_and_b32_e32 v57, 0xffff0000, v50
	v_lshlrev_b32_e32 v58, 16, v51
	v_and_b32_e32 v59, 0xffff0000, v51
	v_pk_mul_f32 v[56:57], v[54:55], v[56:57] op_sel_hi:[0,1]
	v_pk_mul_f32 v[58:59], v[54:55], v[58:59] op_sel_hi:[0,1]
	v_pk_mul_f32 v[56:57], v[32:33], v[56:57]
	v_pk_mul_f32 v[58:59], v[34:35], v[58:59]
	global_store_dwordx4 v[6:7], v[56:59], off offset:-16 nt
	v_lshlrev_b32_e32 v60, 16, v52
	v_and_b32_e32 v61, 0xffff0000, v52
	v_lshlrev_b32_e32 v62, 16, v53
	v_and_b32_e32 v63, 0xffff0000, v53
	v_pk_mul_f32 v[60:61], v[54:55], v[60:61] op_sel_hi:[0,1]
	v_pk_mul_f32 v[62:63], v[54:55], v[62:63] op_sel_hi:[0,1]
	v_pk_mul_f32 v[60:61], v[36:37], v[60:61]
	v_pk_mul_f32 v[62:63], v[38:39], v[62:63]
	global_store_dwordx4 v[6:7], v[60:63], off nt
	v_ffbh_u32_e32 v102, v75
	v_min_u32_e32 v102, 32, v102
	v_lshlrev_b64 v[104:105], v102, v[74:75]
	v_min_u32_e32 v104, 1, v104
	v_or_b32_e32 v104, v105, v104
	v_cvt_f32_u32_e32 v104, v104
	v_sub_u32_e32 v102, 32, v102
	v_ldexp_f32 v104, v104, v102
	v_mul_f32_e32 v104, 0x37800000, v104
	v_fmamk_f32 v104, v104, 0x3a800000, v0
	v_rsq_f32_e32 v100, v104
	v_lshlrev_b32_e32 v84, 16, v76
	v_and_b32_e32 v85, 0xffff0000, v76
	v_lshlrev_b32_e32 v86, 16, v77
	v_and_b32_e32 v87, 0xffff0000, v77
	v_pk_mul_f32 v[84:85], v[100:101], v[84:85] op_sel_hi:[0,1]
	v_pk_mul_f32 v[86:87], v[100:101], v[86:87] op_sel_hi:[0,1]
	v_pk_mul_f32 v[84:85], v[24:25], v[84:85]
	v_pk_mul_f32 v[86:87], v[26:27], v[86:87]
	global_store_dwordx4 v[108:109], v[84:87], off offset:-2064 nt
	v_lshlrev_b32_e32 v88, 16, v78
	v_and_b32_e32 v89, 0xffff0000, v78
	v_lshlrev_b32_e32 v90, 16, v79
	v_and_b32_e32 v91, 0xffff0000, v79
	v_pk_mul_f32 v[88:89], v[100:101], v[88:89] op_sel_hi:[0,1]
	v_pk_mul_f32 v[90:91], v[100:101], v[90:91] op_sel_hi:[0,1]
	v_pk_mul_f32 v[88:89], v[28:29], v[88:89]
	v_pk_mul_f32 v[90:91], v[30:31], v[90:91]
	global_store_dwordx4 v[108:109], v[88:91], off offset:-2048 nt
	v_lshlrev_b32_e32 v92, 16, v80
	v_and_b32_e32 v93, 0xffff0000, v80
	v_lshlrev_b32_e32 v94, 16, v81
	v_and_b32_e32 v95, 0xffff0000, v81
	v_pk_mul_f32 v[92:93], v[100:101], v[92:93] op_sel_hi:[0,1]
	v_pk_mul_f32 v[94:95], v[100:101], v[94:95] op_sel_hi:[0,1]
	v_pk_mul_f32 v[92:93], v[32:33], v[92:93]
	v_pk_mul_f32 v[94:95], v[34:35], v[94:95]
	global_store_dwordx4 v[108:109], v[92:95], off offset:-16 nt
	v_lshlrev_b32_e32 v96, 16, v82
	v_and_b32_e32 v97, 0xffff0000, v82
	v_lshlrev_b32_e32 v98, 16, v83
	v_and_b32_e32 v99, 0xffff0000, v83
	v_pk_mul_f32 v[96:97], v[100:101], v[96:97] op_sel_hi:[0,1]
	v_pk_mul_f32 v[98:99], v[100:101], v[98:99] op_sel_hi:[0,1]
	v_pk_mul_f32 v[96:97], v[36:37], v[96:97]
	v_pk_mul_f32 v[98:99], v[38:39], v[98:99]
	global_store_dwordx4 v[108:109], v[96:99], off nt
	v_lshl_add_u64 v[6:7], v[108:109], 0, s[4:5]
	s_cmp_eq_u32 s14, 0
	s_cbranch_scc1 .Lfn_loop
